# v039 + attention: waves 4-7 spread their LDS-DMA pieces over twice as many MFMA gaps (K pieces in alternate gaps of PV(HF=1), V pieces in alternate gaps of their next PV(HF=0))
# baseline (speedup 1.0000x reference)
.LBB0_597:
	s_setprio 0
	s_waitcnt lgkmcnt(0)
	s_and_b64 vcc, exec, s[98:99]
	v_cvt_pk_bf16_f32 v96, v112, v113
	v_cvt_pk_bf16_f32 v97, v116, v115
	v_cvt_pk_bf16_f32 v98, v118, v119
	v_cvt_pk_bf16_f32 v99, v120, v117
	v_cvt_pk_bf16_f32 v100, v114, v121
	v_cvt_pk_bf16_f32 v101, v122, v123
	v_cvt_pk_bf16_f32 v102, v124, v125
	v_cvt_pk_bf16_f32 v103, v126, v127
	ds_read_b64_tr_b16 v[104:105], v244 offset:61440
	ds_read_b64_tr_b16 v[106:107], v244 offset:63488
	ds_read_b64_tr_b16 v[108:109], v245 offset:61440
	ds_read_b64_tr_b16 v[110:111], v245 offset:63488
	ds_read_b64_tr_b16 v[112:113], v246 offset:61440
	ds_read_b64_tr_b16 v[114:115], v246 offset:63488
	ds_read_b64_tr_b16 v[116:117], v247 offset:61440
	ds_read_b64_tr_b16 v[118:119], v247 offset:63488
	s_add_i32 s65, s65, 1
	s_add_u32 s36, s36, 0x10000
	s_addc_u32 s37, s37, 0
	s_addk_i32 s69, 0x4000
	s_add_i32 s70, s70, 64
	s_add_u32 s38, s38, 0x10000
	s_addc_u32 s39, s39, 0
	s_add_i32 s71, s71, 1
	s_add_i32 s46, s46, 1
	v_add_f32_e32 v162, v163, v162
	s_cbranch_vccz .Lat_lower
	s_mul_i32 s0, s65, 0xab
	s_bfe_u32 s0, s0, 0x70009
	s_mul_i32 s0, s0, 3
	s_sub_i32 s0, s65, s0
	s_and_b32 s0, s0, 0xff
	s_lshl_b32 s0, s0, 14
	s_add_i32 s0, s82, s0
	s_sub_u32 s100, s36, 0x4000
	s_subb_u32 s101, s37, 0
	s_waitcnt vmcnt(0) lgkmcnt(0)
	s_barrier
	v_mfma_f32_32x32x16_bf16 v[48:63], v[228:231], v[96:99], v[48:63]
	s_mov_b32 m0, s0
	s_add_i32 s1, s0, 0x2000
	global_load_lds_dwordx4 v174, s[36:37]
	v_mfma_f32_32x32x16_bf16 v[32:47], v[232:235], v[96:99], v[32:47]
	v_mfma_f32_32x32x16_bf16 v[16:31], v[236:239], v[96:99], v[16:31]
	s_mov_b32 m0, s1
	s_add_i32 s1, s0, 0xfffff000
	global_load_lds_dwordx4 v180, s[36:37]
	v_mfma_f32_32x32x16_bf16 v[0:15], v[240:243], v[96:99], v[0:15]
	v_mfma_f32_32x32x16_bf16 v[48:63], v[104:107], v[100:103], v[48:63]
	s_mov_b32 m0, s1
	s_add_i32 s1, s1, 0x2000
	global_load_lds_dwordx4 v174, s[100:101]
	v_mfma_f32_32x32x16_bf16 v[32:47], v[108:111], v[100:103], v[32:47]
	v_mfma_f32_32x32x16_bf16 v[16:31], v[112:115], v[100:103], v[16:31]
	s_mov_b32 m0, s1
	s_nop 0
	global_load_lds_dwordx4 v180, s[100:101]
	v_mfma_f32_32x32x16_bf16 v[0:15], v[116:119], v[100:103], v[0:15]
	s_branch .Lat_join

.LBB0_607:
	s_setprio 0
	s_cmp_lg_u64 s[98:99], 0
	s_cbranch_scc1 .Lpv0_up
	s_waitcnt lgkmcnt(0)
	v_cvt_pk_bf16_f32 v80, v112, v113
	v_cvt_pk_bf16_f32 v81, v114, v115
	v_cvt_pk_bf16_f32 v82, v116, v117
	v_cvt_pk_bf16_f32 v83, v118, v119
	ds_read_b64_tr_b16 v[88:89], v244 offset:53248
	ds_read_b64_tr_b16 v[90:91], v244 offset:55296
	ds_read_b64_tr_b16 v[92:93], v245 offset:53248
	ds_read_b64_tr_b16 v[94:95], v245 offset:55296
	v_cvt_pk_bf16_f32 v84, v120, v121
	v_cvt_pk_bf16_f32 v85, v122, v123
	v_cvt_pk_bf16_f32 v86, v124, v125
	v_cvt_pk_bf16_f32 v87, v126, v127
	ds_read_b64_tr_b16 v[112:113], v246 offset:53248
	ds_read_b64_tr_b16 v[114:115], v246 offset:55296
	ds_read_b64_tr_b16 v[116:117], v247 offset:53248
	ds_read_b64_tr_b16 v[118:119], v247 offset:55296
	s_waitcnt lgkmcnt(8)
	v_mfma_f32_32x32x16_bf16 v[48:63], v[228:231], v[80:83], v[48:63]
	s_cmp_gt_u32 s70, s66
	s_cselect_b64 s[0:1], -1, 0
	s_and_b64 s[8:9], s[0:1], exec
	s_cselect_b32 s61, 2, 1
	v_mfma_f32_32x32x16_bf16 v[32:47], v[232:235], v[80:83], v[32:47]
	s_cmp_gt_i32 s70, s68
	s_cselect_b64 vcc, -1, 0
	s_and_b64 s[8:9], vcc, exec
	s_cselect_b32 s61, s61, 0
	v_mfma_f32_32x32x16_bf16 v[16:31], v[236:239], v[80:83], v[16:31]
	s_cmp_eq_u32 s61, s60
	v_mfma_f32_32x32x16_bf16 v[0:15], v[240:243], v[80:83], v[0:15]
	s_waitcnt lgkmcnt(6)
	v_mfma_f32_32x32x16_bf16 v[48:63], v[88:91], v[84:87], v[48:63]
	s_waitcnt lgkmcnt(4)
	v_mfma_f32_32x32x16_bf16 v[32:47], v[92:95], v[84:87], v[32:47]
	s_waitcnt lgkmcnt(2)
	v_mfma_f32_32x32x16_bf16 v[16:31], v[112:115], v[84:87], v[16:31]
	s_waitcnt lgkmcnt(0)
	v_mfma_f32_32x32x16_bf16 v[0:15], v[116:119], v[84:87], v[0:15]
	s_cbranch_scc1 .LBB0_609
.Lpv0_608:
	s_and_b64 s[8:9], vcc, s[0:1]
	v_cndmask_b32_e64 v80, 0, v161, s[8:9]
	s_cmp_eq_u32 s60, 0
	v_cndmask_b32_e32 v80, v160, v80, vcc
	s_cselect_b64 vcc, -1, 0
	s_cmp_eq_u32 s60, 2
	s_cselect_b64 s[8:9], -1, 0
	v_cndmask_b32_e64 v81, 0, v161, s[8:9]
	v_cndmask_b32_e32 v81, v81, v160, vcc
	v_sub_f32_e32 v80, v80, v81
	v_pk_add_f32 v[78:79], v[80:81], v[78:79] op_sel_hi:[0,1]
	v_pk_add_f32 v[76:77], v[80:81], v[76:77] op_sel_hi:[0,1]
	v_pk_add_f32 v[74:75], v[80:81], v[74:75] op_sel_hi:[0,1]
	v_pk_add_f32 v[72:73], v[80:81], v[72:73] op_sel_hi:[0,1]
	v_pk_add_f32 v[70:71], v[80:81], v[70:71] op_sel_hi:[0,1]
	v_pk_add_f32 v[68:69], v[80:81], v[68:69] op_sel_hi:[0,1]
	v_pk_add_f32 v[66:67], v[80:81], v[66:67] op_sel_hi:[0,1]
	v_pk_add_f32 v[64:65], v[80:81], v[64:65] op_sel_hi:[0,1]
	s_branch .LBB0_610

; #define AT_WAIT_BAR() asm volatile("s_waitcnt vmcnt(0) lgkmcnt(0)\n\ts_barrier" ::: "memory")
; #define AT_DMAK(t_) do { const bf16_t* gb_ = kgb + (size_t)(t_) * 64 * 512; const unsigned d_ = (unsigned)__builtin_amdgcn_readfirstlane(lds0 + ((t_) % 3) * AT_KB + dmaoff); glds16(kvo0, gb_, d_); glds16(kvo1, gb_, d_ + 8192u); } while (0)
; #define AT_DMAV(t_) do { const bf16_t* gb_ = vgb + (size_t)(t_) * 64 * 512; const unsigned d_ = (unsigned)__builtin_amdgcn_readfirstlane(lds0 + AT_V0 + ((t_) & 1) * AT_VB + dmaoff); glds16(vvo0, gb_, d_); glds16(vvo1, gb_, d_ + 8192u); } while (0)
; __device__ __forceinline__ void attn_phase(LAS unsigned char* lds, const bf16_t* QA, const bf16_t* KA, const bf16_t* VA, bf16_t* CAT, const bf16_t* OF, const bf16_t* OB, const bf16_t* GR, const float* rnorm, ...
;     ...
;         AT_DMAK(0); AT_DMAV(0); AT_DMAK(1);
;         AT_WAIT_BAR();
;         const float bleft = tab[hd * 324 + 0], bright = tab[hd * 324 + 320];
;     ...
;         int ccls = 1;
.Lpv0_up:
	s_waitcnt lgkmcnt(0)
	v_cvt_pk_bf16_f32 v80, v112, v113
	v_cvt_pk_bf16_f32 v81, v114, v115
	v_cvt_pk_bf16_f32 v82, v116, v117
	v_cvt_pk_bf16_f32 v83, v118, v119
	ds_read_b64_tr_b16 v[88:89], v244 offset:53248
	ds_read_b64_tr_b16 v[90:91], v244 offset:55296
	ds_read_b64_tr_b16 v[92:93], v245 offset:53248
	ds_read_b64_tr_b16 v[94:95], v245 offset:55296
	v_cvt_pk_bf16_f32 v84, v120, v121
	v_cvt_pk_bf16_f32 v85, v122, v123
	v_cvt_pk_bf16_f32 v86, v124, v125
	v_cvt_pk_bf16_f32 v87, v126, v127
	ds_read_b64_tr_b16 v[112:113], v246 offset:53248
	ds_read_b64_tr_b16 v[114:115], v246 offset:55296
	ds_read_b64_tr_b16 v[116:117], v247 offset:53248
	ds_read_b64_tr_b16 v[118:119], v247 offset:55296
	s_cmp_gt_u32 s70, s66
	s_cselect_b64 s[0:1], -1, 0
	s_and_b64 s[8:9], s[0:1], exec
	s_cselect_b32 s61, 2, 1
	s_cmp_gt_i32 s70, s68
	s_cselect_b64 vcc, -1, 0
	s_and_b64 s[8:9], vcc, exec
	s_cselect_b32 s61, s61, 0
	s_and_b32 s8, s69, 0x4000
	s_add_i32 s8, s83, s8
	s_sub_u32 s100, s38, 0x4000
	s_subb_u32 s101, s39, 0
	s_waitcnt lgkmcnt(8)
	v_mfma_f32_32x32x16_bf16 v[48:63], v[228:231], v[80:83], v[48:63]
	s_mov_b32 m0, s8
	s_add_i32 s9, s8, 0x2000
	global_load_lds_dwordx4 v175, s[38:39]
	v_mfma_f32_32x32x16_bf16 v[32:47], v[232:235], v[80:83], v[32:47]
	v_mfma_f32_32x32x16_bf16 v[16:31], v[236:239], v[80:83], v[16:31]
	s_mov_b32 m0, s9
	s_add_i32 s9, s8, 0xfffff000
	global_load_lds_dwordx4 v181, s[38:39]
	v_mfma_f32_32x32x16_bf16 v[0:15], v[240:243], v[80:83], v[0:15]
	s_waitcnt lgkmcnt(6)
	v_mfma_f32_32x32x16_bf16 v[48:63], v[88:91], v[84:87], v[48:63]
	s_mov_b32 m0, s9
	s_add_i32 s9, s9, 0x2000
	global_load_lds_dwordx4 v175, s[100:101]
	s_waitcnt lgkmcnt(4)
	v_mfma_f32_32x32x16_bf16 v[32:47], v[92:95], v[84:87], v[32:47]
	s_waitcnt lgkmcnt(2)
	v_mfma_f32_32x32x16_bf16 v[16:31], v[112:115], v[84:87], v[16:31]
	s_mov_b32 m0, s9
	s_nop 0
	global_load_lds_dwordx4 v181, s[100:101]
	s_waitcnt lgkmcnt(0)
	v_mfma_f32_32x32x16_bf16 v[0:15], v[116:119], v[84:87], v[0:15]
	s_cmp_eq_u32 s61, s60
	s_cbranch_scc1 .LBB0_609
	s_branch .Lpv0_608
